# P9b mem-k per-head norm: the 4 items per wave issue their loads up front (was 4 serialized load-wait-store round trips)
# speedup vs baseline: 1.0066x; 1.0066x over previous
; __device__ __forceinline__ unsigned pk2(float lo, float hi) { f32x2_t v = {lo, hi}; bf16x2_t b = __builtin_convertvector(v, bf16x2_t); return __builtin_bit_cast(unsigned, b); }
; __device__ __forceinline__ void norm128(bf16_t* p, const float* g, float oscale, int lane) {
;     const unsigned u = ((const unsigned*)p)[lane]; const float a0 = bflo(u), a1 = bfhi(u);
;     const float ss = wave_sum(a0 * a0 + a1 * a1);
;     const float r = rsqrtf(ss * (1.f / 128.f) + EPS) * oscale;
;     ((unsigned*)p)[lane] = pk2(a0 * r * g[2 * lane], a1 * r * g[2 * lane + 1]);
; }
; __global__ void __launch_bounds__(512, 2) mega_fwd(Args args) {
;     ...
;         for (int it = gw; it < NB * 256 * 4; it += NGW) norm128(MK + (size_t)(it >> 2) * 512 + (it & 3) * 128, args.in[26], 1.f, lane);
.LBB0_1409:
	s_cmp_lt_i32 s92, 11
	s_cselect_b64 s[2:3], -1, 0
	s_add_u32 s64, s86, 0x1c800000
	s_addc_u32 s65, s87, 0
	s_and_b64 s[0:1], s[2:3], s[0:1]
	s_andn2_b64 vcc, exec, s[0:1]
	s_cbranch_vccnz .LBB0_1528
	s_cmpk_gt_i32 s82, 0x1fff
	s_cbranch_scc1 .LBB0_1413
	v_lshlrev_b32_e32 v0, 3, v184
	global_load_dwordx2 v[0:1], v0, s[20:21]
	s_lshl_b32 s2, s80, 10
	s_lshl_b32 s3, s90, 7
	s_add_i32 s2, s2, s3
	s_lshl_b32 s3, s15, 10
	s_waitcnt vmcnt(0)
	v_lshlrev_b32_e32 v2, 2, v184
	v_mov_b32_e32 v3, 0x358637bd
	s_mov_b32 s6, 0x800000
	s_cmp_lg_u32 s96, 0x800
	s_cbranch_scc1 .LBB0_1412
	s_cmpk_gt_i32 s82, 0x7ff
	s_cbranch_scc1 .LBB0_1412
	s_ashr_i32 s12, s82, 2
	s_ashr_i32 s13, s12, 31
	s_lshl_b64 s[12:13], s[12:13], 10
	s_add_u32 s7, s22, s12
	s_addc_u32 s13, s23, s13
	s_and_b32 s12, s2, 0x180
	s_lshl_b32 s12, s12, 1
	s_add_u32 s8, s7, s12
	s_addc_u32 s9, s13, 0
	global_load_dword v5, v2, s[8:9]
	s_add_i32 s82, s82, s96
	s_add_i32 s2, s2, s3
	s_ashr_i32 s12, s82, 2
	s_ashr_i32 s13, s12, 31
	s_lshl_b64 s[12:13], s[12:13], 10
	s_add_u32 s7, s22, s12
	s_addc_u32 s13, s23, s13
	s_and_b32 s12, s2, 0x180
	s_lshl_b32 s12, s12, 1
	s_add_u32 s16, s7, s12
	s_addc_u32 s17, s13, 0
	global_load_dword v8, v2, s[16:17]
	s_add_i32 s82, s82, s96
	s_add_i32 s2, s2, s3
	s_ashr_i32 s12, s82, 2
	s_ashr_i32 s13, s12, 31
	s_lshl_b64 s[12:13], s[12:13], 10
	s_add_u32 s7, s22, s12
	s_addc_u32 s13, s23, s13
	s_and_b32 s12, s2, 0x180
	s_lshl_b32 s12, s12, 1
	s_add_u32 s32, s7, s12
	s_addc_u32 s33, s13, 0
	global_load_dword v9, v2, s[32:33]
	s_add_i32 s82, s82, s96
	s_add_i32 s2, s2, s3
	s_ashr_i32 s12, s82, 2
	s_ashr_i32 s13, s12, 31
	s_lshl_b64 s[12:13], s[12:13], 10
	s_add_u32 s7, s22, s12
	s_addc_u32 s13, s23, s13
	s_and_b32 s12, s2, 0x180
	s_lshl_b32 s12, s12, 1
	s_add_u32 s34, s7, s12
	s_addc_u32 s35, s13, 0
	global_load_dword v10, v2, s[34:35]
	s_add_i32 s82, s82, s96
	s_add_i32 s2, s2, s3
	s_waitcnt vmcnt(3)
	v_lshlrev_b32_e32 v4, 16, v5
	v_and_b32_e32 v5, 0xffff0000, v5
	v_pk_mul_f32 v[6:7], v[4:5], v[4:5]
	s_nop 0
	v_add_f32_e32 v6, v6, v7
	s_nop 1
	v_add_f32_dpp v6, v6, v6 quad_perm:[1,0,3,2] row_mask:0xf bank_mask:0xf bound_ctrl:1
	s_nop 1
	v_add_f32_dpp v6, v6, v6 quad_perm:[2,3,0,1] row_mask:0xf bank_mask:0xf bound_ctrl:1
	s_nop 1
	v_add_f32_dpp v6, v6, v6 row_half_mirror row_mask:0xf bank_mask:0xf bound_ctrl:1
	s_nop 1
	v_add_f32_dpp v6, v6, v6 row_mirror row_mask:0xf bank_mask:0xf bound_ctrl:1
	s_nop 0
	v_readlane_b32 s7, v6, 16
	v_readlane_b32 s14, v6, 48
	v_readlane_b32 s12, v6, 0
	v_readlane_b32 s13, v6, 32
	v_mov_b32_e32 v6, s7
	v_mov_b32_e32 v7, s14
	v_pk_add_f32 v[6:7], s[12:13], v[6:7]
	s_nop 0
	v_add_f32_e32 v6, v6, v7
	v_fmamk_f32 v6, v6, 0x3c000000, v3
	v_mul_f32_e32 v7, 0x4b800000, v6
	v_cmp_gt_f32_e32 vcc, s6, v6
	s_nop 1
	v_cndmask_b32_e32 v6, v6, v7, vcc
	v_rsq_f32_e32 v6, v6
	s_nop 0
	v_mul_f32_e32 v7, 0x45800000, v6
	v_cndmask_b32_e32 v6, v6, v7, vcc
	v_pk_mul_f32 v[4:5], v[6:7], v[4:5] op_sel_hi:[0,1]
	v_pk_mul_f32 v[4:5], v[0:1], v[4:5]
	s_nop 0
	v_cvt_pk_bf16_f32 v4, v4, v5
	global_store_dword v2, v4, s[8:9]
	s_waitcnt vmcnt(3)
	v_lshlrev_b32_e32 v4, 16, v8
	v_and_b32_e32 v5, 0xffff0000, v8
	v_pk_mul_f32 v[6:7], v[4:5], v[4:5]
	s_nop 0
	v_add_f32_e32 v6, v6, v7
	s_nop 1
	v_add_f32_dpp v6, v6, v6 quad_perm:[1,0,3,2] row_mask:0xf bank_mask:0xf bound_ctrl:1
	s_nop 1
	v_add_f32_dpp v6, v6, v6 quad_perm:[2,3,0,1] row_mask:0xf bank_mask:0xf bound_ctrl:1
	s_nop 1
	v_add_f32_dpp v6, v6, v6 row_half_mirror row_mask:0xf bank_mask:0xf bound_ctrl:1
	s_nop 1
	v_add_f32_dpp v6, v6, v6 row_mirror row_mask:0xf bank_mask:0xf bound_ctrl:1
	s_nop 0
	v_readlane_b32 s7, v6, 16
	v_readlane_b32 s14, v6, 48
	v_readlane_b32 s12, v6, 0
	v_readlane_b32 s13, v6, 32
	v_mov_b32_e32 v6, s7
	v_mov_b32_e32 v7, s14
	v_pk_add_f32 v[6:7], s[12:13], v[6:7]
	s_nop 0
	v_add_f32_e32 v6, v6, v7
	v_fmamk_f32 v6, v6, 0x3c000000, v3
	v_mul_f32_e32 v7, 0x4b800000, v6
	v_cmp_gt_f32_e32 vcc, s6, v6
	s_nop 1
	v_cndmask_b32_e32 v6, v6, v7, vcc
	v_rsq_f32_e32 v6, v6
	s_nop 0
	v_mul_f32_e32 v7, 0x45800000, v6
	v_cndmask_b32_e32 v6, v6, v7, vcc
	v_pk_mul_f32 v[4:5], v[6:7], v[4:5] op_sel_hi:[0,1]
	v_pk_mul_f32 v[4:5], v[0:1], v[4:5]
	s_nop 0
	v_cvt_pk_bf16_f32 v4, v4, v5
	global_store_dword v2, v4, s[16:17]
	s_waitcnt vmcnt(3)
	v_lshlrev_b32_e32 v4, 16, v9
	v_and_b32_e32 v5, 0xffff0000, v9
	v_pk_mul_f32 v[6:7], v[4:5], v[4:5]
	s_nop 0
	v_add_f32_e32 v6, v6, v7
	s_nop 1
	v_add_f32_dpp v6, v6, v6 quad_perm:[1,0,3,2] row_mask:0xf bank_mask:0xf bound_ctrl:1
	s_nop 1
	v_add_f32_dpp v6, v6, v6 quad_perm:[2,3,0,1] row_mask:0xf bank_mask:0xf bound_ctrl:1
	s_nop 1
	v_add_f32_dpp v6, v6, v6 row_half_mirror row_mask:0xf bank_mask:0xf bound_ctrl:1
	s_nop 1
	v_add_f32_dpp v6, v6, v6 row_mirror row_mask:0xf bank_mask:0xf bound_ctrl:1
	s_nop 0
	v_readlane_b32 s7, v6, 16
	v_readlane_b32 s14, v6, 48
	v_readlane_b32 s12, v6, 0
	v_readlane_b32 s13, v6, 32
	v_mov_b32_e32 v6, s7
	v_mov_b32_e32 v7, s14
	v_pk_add_f32 v[6:7], s[12:13], v[6:7]
	s_nop 0
	v_add_f32_e32 v6, v6, v7
	v_fmamk_f32 v6, v6, 0x3c000000, v3
	v_mul_f32_e32 v7, 0x4b800000, v6
	v_cmp_gt_f32_e32 vcc, s6, v6
	s_nop 1
	v_cndmask_b32_e32 v6, v6, v7, vcc
	v_rsq_f32_e32 v6, v6
	s_nop 0
	v_mul_f32_e32 v7, 0x45800000, v6
	v_cndmask_b32_e32 v6, v6, v7, vcc
	v_pk_mul_f32 v[4:5], v[6:7], v[4:5] op_sel_hi:[0,1]
	v_pk_mul_f32 v[4:5], v[0:1], v[4:5]
	s_nop 0
	v_cvt_pk_bf16_f32 v4, v4, v5
	global_store_dword v2, v4, s[32:33]
	s_waitcnt vmcnt(3)
	v_lshlrev_b32_e32 v4, 16, v10
	v_and_b32_e32 v5, 0xffff0000, v10
	v_pk_mul_f32 v[6:7], v[4:5], v[4:5]
	s_nop 0
	v_add_f32_e32 v6, v6, v7
	s_nop 1
	v_add_f32_dpp v6, v6, v6 quad_perm:[1,0,3,2] row_mask:0xf bank_mask:0xf bound_ctrl:1
	s_nop 1
	v_add_f32_dpp v6, v6, v6 quad_perm:[2,3,0,1] row_mask:0xf bank_mask:0xf bound_ctrl:1
	s_nop 1
	v_add_f32_dpp v6, v6, v6 row_half_mirror row_mask:0xf bank_mask:0xf bound_ctrl:1
	s_nop 1
	v_add_f32_dpp v6, v6, v6 row_mirror row_mask:0xf bank_mask:0xf bound_ctrl:1
	s_nop 0
	v_readlane_b32 s7, v6, 16
	v_readlane_b32 s14, v6, 48
	v_readlane_b32 s12, v6, 0
	v_readlane_b32 s13, v6, 32
	v_mov_b32_e32 v6, s7
	v_mov_b32_e32 v7, s14
	v_pk_add_f32 v[6:7], s[12:13], v[6:7]
	s_nop 0
	v_add_f32_e32 v6, v6, v7
	v_fmamk_f32 v6, v6, 0x3c000000, v3
	v_mul_f32_e32 v7, 0x4b800000, v6
	v_cmp_gt_f32_e32 vcc, s6, v6
	s_nop 1
	v_cndmask_b32_e32 v6, v6, v7, vcc
	v_rsq_f32_e32 v6, v6
	s_nop 0
	v_mul_f32_e32 v7, 0x45800000, v6
	v_cndmask_b32_e32 v6, v6, v7, vcc
	v_pk_mul_f32 v[4:5], v[6:7], v[4:5] op_sel_hi:[0,1]
	v_pk_mul_f32 v[4:5], v[0:1], v[4:5]
	s_nop 0
	v_cvt_pk_bf16_f32 v4, v4, v5
	global_store_dword v2, v4, s[34:35]
	s_branch .LBB0_1413
